# FFN-up epilogue: leading wave-half issues its row-statistics loads before the alignment barrier
# baseline (speedup 1.0000x reference)
; #define PG8_STAGE(bufoff, gbase, voff) do { _Pragma("unroll") for (int _i = 0; _i < 2; ++_i) { \
;         const unsigned _m0 = ldsu + (unsigned)(bufoff) + ldsw + (unsigned)(_i * 8192); \
;         asm volatile("s_mov_b32 m0, %2\n\ts_nop 0\n\tglobal_load_lds_dwordx4 %0, %1" :: "v"((voff)[_i]), "s"((const char*)(gbase)), "s"(_m0) : "memory"); } } while (0)
; #define PG8_LDA(dst, b, h) do { _Pragma("unroll") for (int m = 0; m < 4; ++m) _Pragma("unroll") for (int k = 0; k < 2; ++k) dst[m][k] = *(const LAS bf16x8*)(lds + PG8_SA(b, h) + aoff + m * 2048 + k * 1024); } while (0)
; #define PG8_LDB(dst, b, h) do { _Pragma("unroll") for (int n = 0; n < 2; ++n) _Pragma("unroll") for (int k = 0; k < 2; ++k) dst[n][k] = *(const LAS bf16x8*)(lds + bbase[b][h] + n * 2048 + k * 1024); } while (0)
; #define PG8_WAIT_V(n) asm volatile("s_waitcnt vmcnt(" #n ")" ::: "memory")
; #define PG8_BAR __builtin_amdgcn_s_barrier()
; template <class Epi>
; __device__ __forceinline__ void gemm_phase(LAS unsigned char* lds, const Gemm g, const StaticOrder& S, const Epi& E) {
;     ...
;         for (int t = 0; t < nt; t += 2) {
;             const bool last = (t == nt - 2);
;             const char* a2 = last ? nA : cA + (size_t)(t + 2) * kstep; const char* b2 = last ? nB : cB + (size_t)(t + 2) * kstep;
;             const char* a3 = a2 + kstep; const char* b3 = b2 + kstep;
;             const char* b1 = cB + (size_t)(t + 1) * kstep;
;             PG8_LDB(B0, 0, 0); PG8_SCHED; PG8_LDA(At, 0, 0); PG8_LDA(At2, 0, 1); PG8_STAGE(PG8_SB(1, 1), b1 + hstepB, voffB);
;             PG8_WAIT_V(8); PG8_WAIT_L(0); PG8_BAR; PG8_MMA2B(0, At, At2, B0); PG8_BAR; PG8_SCHED;
;             PG8_LDB(B0, 0, 1); PG8_STAGE(PG8_SB(0, 0), b2, voffB); PG8_STAGE(PG8_SA(0, 0), a2, voffA); PG8_STAGE(PG8_SA(0, 1), a2 + hstepA, voffA);
;             PG8_WAIT_V(8); PG8_WAIT_L(0); PG8_BAR; PG8_MMA2B(1, At, At2, B0); PG8_BAR; PG8_SCHED;
;             PG8_LDB(B0, 1, 0); PG8_SCHED; PG8_LDA(At, 1, 0); PG8_LDA(At2, 1, 1); PG8_STAGE(PG8_SB(0, 1), b2 + hstepB, voffB);
;             PG8_WAIT_V(8); PG8_WAIT_L(0); PG8_BAR; PG8_MMA2B(0, At, At2, B0); PG8_BAR; PG8_SCHED;
;             PG8_LDB(B0, 1, 1); PG8_STAGE(PG8_SB(1, 0), b3, voffB); PG8_STAGE(PG8_SA(1, 0), a3, voffA); PG8_STAGE(PG8_SA(1, 1), a3 + hstepA, voffA);
;             PG8_WAIT_V(8); PG8_WAIT_L(0); PG8_BAR; PG8_MMA2B(1, At, At2, B0); PG8_BAR; PG8_SCHED;
;         }
.LBB0_1027:
	ds_read_b128 v[68:71], v220
	ds_read_b128 v[84:87], v220 offset:1024
	ds_read_b128 v[88:91], v220 offset:2048
	ds_read_b128 v[92:95], v220 offset:3072
	s_add_u32 s12, s10, 0x100
	s_addc_u32 s13, s11, 0
	s_cmp_eq_u32 s69, 12
	s_cselect_b32 s14, s97, vcc_hi
	s_cselect_b32 s15, s7, s68
	s_cselect_b32 s84, vcc_lo, s12
	s_cselect_b32 s85, s39, s13
	s_add_u32 s16, s14, 0x80
	s_addc_u32 s17, s15, 0
	ds_read_b128 v[96:99], v221
	ds_read_b128 v[100:103], v221 offset:1024
	ds_read_b128 v[152:155], v221 offset:2048
	ds_read_b128 v[156:159], v221 offset:3072
	ds_read_b128 v[166:169], v221 offset:4096
	ds_read_b128 v[178:181], v221 offset:5120
	ds_read_b128 v[182:185], v221 offset:6144
	ds_read_b128 v[186:189], v221 offset:7168
	ds_read_b128 v[190:193], v221 offset:16384
	ds_read_b128 v[194:197], v221 offset:17408
	ds_read_b128 v[198:201], v221 offset:18432
	ds_read_b128 v[202:205], v221 offset:19456
	ds_read_b128 v[226:229], v221 offset:20480
	ds_read_b128 v[230:233], v221 offset:21504
	ds_read_b128 v[234:237], v221 offset:22528
	ds_read_b128 v[238:241], v221 offset:23552
	s_add_u32 s10, s10, 0x40080
	s_addc_u32 s11, s11, 0
	s_mov_b32 m0, s58
	s_nop 0
	global_load_lds_dwordx4 v217, s[10:11]
	s_mov_b32 m0, s60
	s_nop 0
	global_load_lds_dwordx4 v219, s[10:11]
	s_waitcnt vmcnt(8)
	s_waitcnt lgkmcnt(0)
	s_barrier
	s_setprio 1
	s_waitcnt lgkmcnt(14)
	v_mfma_f32_16x16x32_bf16 v[80:83], v[68:71], v[96:99], v[80:83]
	v_mfma_f32_16x16x32_bf16 v[76:79], v[88:91], v[96:99], v[76:79]
	s_waitcnt lgkmcnt(13)
	v_mfma_f32_16x16x32_bf16 v[148:151], v[68:71], v[152:155], v[148:151]
	v_mfma_f32_16x16x32_bf16 v[52:55], v[88:91], v[152:155], v[52:55]
	s_waitcnt lgkmcnt(11)
	v_mfma_f32_16x16x32_bf16 v[144:147], v[68:71], v[166:169], v[144:147]
	v_mfma_f32_16x16x32_bf16 v[48:51], v[88:91], v[166:169], v[48:51]
	s_waitcnt lgkmcnt(9)
	v_mfma_f32_16x16x32_bf16 v[136:139], v[68:71], v[182:185], v[136:139]
	v_mfma_f32_16x16x32_bf16 v[40:43], v[88:91], v[182:185], v[40:43]
	s_waitcnt lgkmcnt(7)
	v_mfma_f32_16x16x32_bf16 v[124:127], v[68:71], v[190:193], v[124:127]
	v_mfma_f32_16x16x32_bf16 v[28:31], v[88:91], v[190:193], v[28:31]
	s_waitcnt lgkmcnt(5)
	v_mfma_f32_16x16x32_bf16 v[120:123], v[68:71], v[198:201], v[120:123]
	v_mfma_f32_16x16x32_bf16 v[24:27], v[88:91], v[198:201], v[24:27]
	s_waitcnt lgkmcnt(3)
	v_mfma_f32_16x16x32_bf16 v[112:115], v[68:71], v[226:229], v[112:115]
	v_mfma_f32_16x16x32_bf16 v[16:19], v[88:91], v[226:229], v[16:19]
	s_waitcnt lgkmcnt(1)
	v_mfma_f32_16x16x32_bf16 v[64:67], v[68:71], v[234:237], v[64:67]
	v_mfma_f32_16x16x32_bf16 v[4:7], v[88:91], v[234:237], v[4:7]
	v_mfma_f32_16x16x32_bf16 v[80:83], v[84:87], v[100:103], v[80:83]
	v_mfma_f32_16x16x32_bf16 v[76:79], v[92:95], v[100:103], v[76:79]
	v_mfma_f32_16x16x32_bf16 v[148:151], v[84:87], v[156:159], v[148:151]
	v_mfma_f32_16x16x32_bf16 v[52:55], v[92:95], v[156:159], v[52:55]
	v_mfma_f32_16x16x32_bf16 v[144:147], v[84:87], v[178:181], v[144:147]
	v_mfma_f32_16x16x32_bf16 v[48:51], v[92:95], v[178:181], v[48:51]
	v_mfma_f32_16x16x32_bf16 v[136:139], v[84:87], v[186:189], v[136:139]
	v_mfma_f32_16x16x32_bf16 v[40:43], v[92:95], v[186:189], v[40:43]
	v_mfma_f32_16x16x32_bf16 v[124:127], v[84:87], v[194:197], v[124:127]
	v_mfma_f32_16x16x32_bf16 v[28:31], v[92:95], v[194:197], v[28:31]
	v_mfma_f32_16x16x32_bf16 v[120:123], v[84:87], v[202:205], v[120:123]
	v_mfma_f32_16x16x32_bf16 v[24:27], v[92:95], v[202:205], v[24:27]
	v_mfma_f32_16x16x32_bf16 v[112:115], v[84:87], v[230:233], v[112:115]
	v_mfma_f32_16x16x32_bf16 v[16:19], v[92:95], v[230:233], v[16:19]
	s_waitcnt lgkmcnt(0)
	v_mfma_f32_16x16x32_bf16 v[64:67], v[84:87], v[238:241], v[64:67]
	v_mfma_f32_16x16x32_bf16 v[4:7], v[92:95], v[238:241], v[4:7]
	s_setprio 0
	s_barrier
	ds_read_b128 v[68:71], v222
	ds_read_b128 v[84:87], v222 offset:1024
	ds_read_b128 v[88:91], v222 offset:2048
	ds_read_b128 v[92:95], v222 offset:3072
	s_mov_b32 m0, s48
	s_nop 0
	global_load_lds_dwordx4 v217, s[84:85]
	s_mov_b32 m0, s49
	s_nop 0
	global_load_lds_dwordx4 v219, s[84:85]
	s_mov_b32 m0, s47
	s_nop 0
	global_load_lds_dwordx4 v216, s[14:15]
	s_mov_b32 m0, s50
	s_nop 0
	global_load_lds_dwordx4 v218, s[14:15]
	s_add_u32 s10, s14, 0x40000
	s_addc_u32 s11, s15, 0
	s_mov_b32 m0, s51
	s_nop 0
	global_load_lds_dwordx4 v216, s[10:11]
	s_mov_b32 m0, s52
	s_nop 0
	global_load_lds_dwordx4 v218, s[10:11]
	s_waitcnt vmcnt(8)
	s_waitcnt lgkmcnt(0)
	s_barrier
	s_setprio 1
	s_waitcnt lgkmcnt(3)
	v_mfma_f32_16x16x32_bf16 v[72:75], v[68:71], v[96:99], v[72:75]
	s_waitcnt lgkmcnt(1)
	v_mfma_f32_16x16x32_bf16 v[56:59], v[88:91], v[96:99], v[56:59]
	v_mfma_f32_16x16x32_bf16 v[44:47], v[88:91], v[152:155], v[44:47]
	v_mfma_f32_16x16x32_bf16 v[36:39], v[88:91], v[166:169], v[36:39]
	v_mfma_f32_16x16x32_bf16 v[128:131], v[68:71], v[182:185], v[128:131]
	v_mfma_f32_16x16x32_bf16 v[32:35], v[88:91], v[182:185], v[32:35]
	v_mfma_f32_16x16x32_bf16 v[116:119], v[68:71], v[190:193], v[116:119]
	v_mfma_f32_16x16x32_bf16 v[20:23], v[88:91], v[190:193], v[20:23]
	v_mfma_f32_16x16x32_bf16 v[108:111], v[68:71], v[198:201], v[108:111]
	v_mfma_f32_16x16x32_bf16 v[12:15], v[88:91], v[198:201], v[12:15]
	v_mfma_f32_16x16x32_bf16 v[104:107], v[68:71], v[226:229], v[104:107]
	v_mfma_f32_16x16x32_bf16 v[8:11], v[88:91], v[226:229], v[8:11]
	v_mfma_f32_16x16x32_bf16 v[60:63], v[68:71], v[234:237], v[60:63]
	v_mfma_f32_16x16x32_bf16 v[0:3], v[88:91], v[234:237], v[0:3]
	v_mfma_f32_16x16x32_bf16 v[72:75], v[84:87], v[100:103], v[72:75]
	s_waitcnt lgkmcnt(0)
	v_mfma_f32_16x16x32_bf16 v[56:59], v[92:95], v[100:103], v[56:59]
	v_mfma_f32_16x16x32_bf16 v[96:99], v[68:71], v[152:155], v[140:143]
	v_mfma_f32_16x16x32_bf16 v[44:47], v[92:95], v[156:159], v[44:47]
	v_mfma_f32_16x16x32_bf16 v[100:103], v[68:71], v[166:169], v[132:135]
	v_mfma_f32_16x16x32_bf16 v[36:39], v[92:95], v[178:181], v[36:39]
	v_mfma_f32_16x16x32_bf16 v[128:131], v[84:87], v[186:189], v[128:131]
	v_mfma_f32_16x16x32_bf16 v[32:35], v[92:95], v[186:189], v[32:35]
	v_mfma_f32_16x16x32_bf16 v[116:119], v[84:87], v[194:197], v[116:119]
	v_mfma_f32_16x16x32_bf16 v[20:23], v[92:95], v[194:197], v[20:23]
	v_mfma_f32_16x16x32_bf16 v[108:111], v[84:87], v[202:205], v[108:111]
	v_mfma_f32_16x16x32_bf16 v[12:15], v[92:95], v[202:205], v[12:15]
	v_mfma_f32_16x16x32_bf16 v[104:107], v[84:87], v[230:233], v[104:107]
	v_mfma_f32_16x16x32_bf16 v[8:11], v[92:95], v[230:233], v[8:11]
	v_mfma_f32_16x16x32_bf16 v[60:63], v[84:87], v[238:241], v[60:63]
	v_mfma_f32_16x16x32_bf16 v[0:3], v[92:95], v[238:241], v[0:3]
	v_mfma_f32_16x16x32_bf16 v[96:99], v[84:87], v[156:159], v[96:99]
	v_mfma_f32_16x16x32_bf16 v[100:103], v[84:87], v[178:181], v[100:103]
	s_setprio 0
	s_barrier
; #define PG8_STAGE(bufoff, gbase, voff) do { _Pragma("unroll") for (int _i = 0; _i < 2; ++_i) { \
;         const unsigned _m0 = ldsu + (unsigned)(bufoff) + ldsw + (unsigned)(_i * 8192); \
;         asm volatile("s_mov_b32 m0, %2\n\ts_nop 0\n\tglobal_load_lds_dwordx4 %0, %1" :: "v"((voff)[_i]), "s"((const char*)(gbase)), "s"(_m0) : "memory"); } } while (0)
; #define PG8_LDA(dst, b, h) do { _Pragma("unroll") for (int m = 0; m < 4; ++m) _Pragma("unroll") for (int k = 0; k < 2; ++k) dst[m][k] = *(const LAS bf16x8*)(lds + PG8_SA(b, h) + aoff + m * 2048 + k * 1024); } while (0)
; #define PG8_LDB(dst, b, h) do { _Pragma("unroll") for (int n = 0; n < 2; ++n) _Pragma("unroll") for (int k = 0; k < 2; ++k) dst[n][k] = *(const LAS bf16x8*)(lds + bbase[b][h] + n * 2048 + k * 1024); } while (0)
; #define PG8_WAIT_V(n) asm volatile("s_waitcnt vmcnt(" #n ")" ::: "memory")
; #define PG8_BAR __builtin_amdgcn_s_barrier()
; template <class Epi>
; __device__ __forceinline__ void gemm_phase(LAS unsigned char* lds, const Gemm g, const StaticOrder& S, const Epi& E) {
;     ...
;         for (int t = 0; t < nt; t += 2) {
;             const bool last = (t == nt - 2);
;             const char* a2 = last ? nA : cA + (size_t)(t + 2) * kstep; const char* b2 = last ? nB : cB + (size_t)(t + 2) * kstep;
;             const char* a3 = a2 + kstep; const char* b3 = b2 + kstep;
;             const char* b1 = cB + (size_t)(t + 1) * kstep;
;             PG8_LDB(B0, 0, 0); PG8_SCHED; PG8_LDA(At, 0, 0); PG8_LDA(At2, 0, 1); PG8_STAGE(PG8_SB(1, 1), b1 + hstepB, voffB);
;             PG8_WAIT_V(8); PG8_WAIT_L(0); PG8_BAR; PG8_MMA2B(0, At, At2, B0); PG8_BAR; PG8_SCHED;
;             PG8_LDB(B0, 0, 1); PG8_STAGE(PG8_SB(0, 0), b2, voffB); PG8_STAGE(PG8_SA(0, 0), a2, voffA); PG8_STAGE(PG8_SA(0, 1), a2 + hstepA, voffA);
;             PG8_WAIT_V(8); PG8_WAIT_L(0); PG8_BAR; PG8_MMA2B(1, At, At2, B0); PG8_BAR; PG8_SCHED;
;             PG8_LDB(B0, 1, 0); PG8_SCHED; PG8_LDA(At, 1, 0); PG8_LDA(At2, 1, 1); PG8_STAGE(PG8_SB(0, 1), b2 + hstepB, voffB);
;             PG8_WAIT_V(8); PG8_WAIT_L(0); PG8_BAR; PG8_MMA2B(0, At, At2, B0); PG8_BAR; PG8_SCHED;
;             PG8_LDB(B0, 1, 1); PG8_STAGE(PG8_SB(1, 0), b3, voffB); PG8_STAGE(PG8_SA(1, 0), a3, voffA); PG8_STAGE(PG8_SA(1, 1), a3 + hstepA, voffA);
;             PG8_WAIT_V(8); PG8_WAIT_L(0); PG8_BAR; PG8_MMA2B(1, At, At2, B0); PG8_BAR; PG8_SCHED;
;         }
	ds_read_b128 v[68:71], v223
	ds_read_b128 v[84:87], v223 offset:1024
	ds_read_b128 v[88:91], v223 offset:2048
	ds_read_b128 v[92:95], v223 offset:3072
	ds_read_b128 v[132:135], v221 offset:32768
	ds_read_b128 v[140:143], v221 offset:33792
	ds_read_b128 v[152:155], v221 offset:34816
	ds_read_b128 v[156:159], v221 offset:35840
	ds_read_b128 v[166:169], v221 offset:36864
	ds_read_b128 v[178:181], v221 offset:37888
	ds_read_b128 v[182:185], v221 offset:38912
	ds_read_b128 v[186:189], v221 offset:39936
	ds_read_b128 v[190:193], v221 offset:49152
	ds_read_b128 v[194:197], v221 offset:50176
	ds_read_b128 v[198:201], v221 offset:51200
	ds_read_b128 v[202:205], v221 offset:52224
	ds_read_b128 v[226:229], v221 offset:53248
	ds_read_b128 v[230:233], v221 offset:54272
	ds_read_b128 v[234:237], v221 offset:55296
	ds_read_b128 v[238:241], v221 offset:56320
	s_add_u32 s10, s84, 0x40000
	s_addc_u32 s11, s85, 0
	s_mov_b32 m0, s53
	s_nop 0
	global_load_lds_dwordx4 v217, s[10:11]
	s_mov_b32 m0, s54
	s_nop 0
	global_load_lds_dwordx4 v219, s[10:11]
	s_waitcnt vmcnt(8)
	s_waitcnt lgkmcnt(0)
	s_barrier
	s_setprio 1
	s_waitcnt lgkmcnt(14)
	v_mfma_f32_16x16x32_bf16 v[80:83], v[68:71], v[132:135], v[80:83]
	v_mfma_f32_16x16x32_bf16 v[76:79], v[88:91], v[132:135], v[76:79]
	s_waitcnt lgkmcnt(13)
	v_mfma_f32_16x16x32_bf16 v[148:151], v[68:71], v[152:155], v[148:151]
	v_mfma_f32_16x16x32_bf16 v[52:55], v[88:91], v[152:155], v[52:55]
	s_waitcnt lgkmcnt(11)
	v_mfma_f32_16x16x32_bf16 v[144:147], v[68:71], v[166:169], v[144:147]
	v_mfma_f32_16x16x32_bf16 v[48:51], v[88:91], v[166:169], v[48:51]
	s_waitcnt lgkmcnt(9)
	v_mfma_f32_16x16x32_bf16 v[136:139], v[68:71], v[182:185], v[136:139]
	v_mfma_f32_16x16x32_bf16 v[40:43], v[88:91], v[182:185], v[40:43]
	s_waitcnt lgkmcnt(7)
	v_mfma_f32_16x16x32_bf16 v[124:127], v[68:71], v[190:193], v[124:127]
	v_mfma_f32_16x16x32_bf16 v[28:31], v[88:91], v[190:193], v[28:31]
	s_waitcnt lgkmcnt(5)
	v_mfma_f32_16x16x32_bf16 v[120:123], v[68:71], v[198:201], v[120:123]
	v_mfma_f32_16x16x32_bf16 v[24:27], v[88:91], v[198:201], v[24:27]
	s_waitcnt lgkmcnt(3)
	v_mfma_f32_16x16x32_bf16 v[112:115], v[68:71], v[226:229], v[112:115]
	v_mfma_f32_16x16x32_bf16 v[16:19], v[88:91], v[226:229], v[16:19]
	s_waitcnt lgkmcnt(1)
	v_mfma_f32_16x16x32_bf16 v[64:67], v[68:71], v[234:237], v[64:67]
	v_mfma_f32_16x16x32_bf16 v[4:7], v[88:91], v[234:237], v[4:7]
	v_mfma_f32_16x16x32_bf16 v[80:83], v[84:87], v[140:143], v[80:83]
	v_mfma_f32_16x16x32_bf16 v[76:79], v[92:95], v[140:143], v[76:79]
	v_mfma_f32_16x16x32_bf16 v[148:151], v[84:87], v[156:159], v[148:151]
	v_mfma_f32_16x16x32_bf16 v[52:55], v[92:95], v[156:159], v[52:55]
	v_mfma_f32_16x16x32_bf16 v[144:147], v[84:87], v[178:181], v[144:147]
	v_mfma_f32_16x16x32_bf16 v[48:51], v[92:95], v[178:181], v[48:51]
	v_mfma_f32_16x16x32_bf16 v[136:139], v[84:87], v[186:189], v[136:139]
	v_mfma_f32_16x16x32_bf16 v[40:43], v[92:95], v[186:189], v[40:43]
	v_mfma_f32_16x16x32_bf16 v[124:127], v[84:87], v[194:197], v[124:127]
	v_mfma_f32_16x16x32_bf16 v[28:31], v[92:95], v[194:197], v[28:31]
	v_mfma_f32_16x16x32_bf16 v[120:123], v[84:87], v[202:205], v[120:123]
	v_mfma_f32_16x16x32_bf16 v[24:27], v[92:95], v[202:205], v[24:27]
	v_mfma_f32_16x16x32_bf16 v[112:115], v[84:87], v[230:233], v[112:115]
	v_mfma_f32_16x16x32_bf16 v[16:19], v[92:95], v[230:233], v[16:19]
	s_waitcnt lgkmcnt(0)
	v_mfma_f32_16x16x32_bf16 v[64:67], v[84:87], v[238:241], v[64:67]
	v_mfma_f32_16x16x32_bf16 v[4:7], v[92:95], v[238:241], v[4:7]
	s_setprio 0
	s_barrier
; #define PG8_STAGE(bufoff, gbase, voff) do { _Pragma("unroll") for (int _i = 0; _i < 2; ++_i) { \
;         const unsigned _m0 = ldsu + (unsigned)(bufoff) + ldsw + (unsigned)(_i * 8192); \
;         asm volatile("s_mov_b32 m0, %2\n\ts_nop 0\n\tglobal_load_lds_dwordx4 %0, %1" :: "v"((voff)[_i]), "s"((const char*)(gbase)), "s"(_m0) : "memory"); } } while (0)
; template <class Epi>
; __device__ __forceinline__ void gemm_phase(LAS unsigned char* lds, const Gemm g, const StaticOrder& S, const Epi& E) {
;     ...
;         for (int t = 0; t < nt; t += 2) {
;             const bool last = (t == nt - 2);
;             const char* a2 = last ? nA : cA + (size_t)(t + 2) * kstep; const char* b2 = last ? nB : cB + (size_t)(t + 2) * kstep;
;             const char* a3 = a2 + kstep; const char* b3 = b2 + kstep;
;             const char* b1 = cB + (size_t)(t + 1) * kstep;
;             PG8_LDB(B0, 0, 0); PG8_SCHED; PG8_LDA(At, 0, 0); PG8_LDA(At2, 0, 1); PG8_STAGE(PG8_SB(1, 1), b1 + hstepB, voffB);
;             PG8_WAIT_V(8); PG8_WAIT_L(0); PG8_BAR; PG8_MMA2B(0, At, At2, B0); PG8_BAR; PG8_SCHED;
;             PG8_LDB(B0, 0, 1); PG8_STAGE(PG8_SB(0, 0), b2, voffB); PG8_STAGE(PG8_SA(0, 0), a2, voffA); PG8_STAGE(PG8_SA(0, 1), a2 + hstepA, voffA);
;             PG8_WAIT_V(8); PG8_WAIT_L(0); PG8_BAR; PG8_MMA2B(1, At, At2, B0); PG8_BAR; PG8_SCHED;
;             PG8_LDB(B0, 1, 0); PG8_SCHED; PG8_LDA(At, 1, 0); PG8_LDA(At2, 1, 1); PG8_STAGE(PG8_SB(0, 1), b2 + hstepB, voffB);
;             PG8_WAIT_V(8); PG8_WAIT_L(0); PG8_BAR; PG8_MMA2B(0, At, At2, B0); PG8_BAR; PG8_SCHED;
;             PG8_LDB(B0, 1, 1); PG8_STAGE(PG8_SB(1, 0), b3, voffB); PG8_STAGE(PG8_SA(1, 0), a3, voffA); PG8_STAGE(PG8_SA(1, 1), a3 + hstepA, voffA);
;             PG8_WAIT_V(8); PG8_WAIT_L(0); PG8_BAR; PG8_MMA2B(1, At, At2, B0); PG8_BAR; PG8_SCHED;
;         }
;         if (wr == 0) PG8_BAR;
;     __device__ __forceinline__ void operator()(f32x4 (&acc)[2][2][4][2], const Unit& u, int wr, int wc, int fr, int fq) const {
;     ...
;         { const int t = (wc * 4 + fq) * 16 + fr;
;           if (wr == 0) { const float* sp = ssq + ((size_t)u.pm * 256 + t) * 16; const f32x4 a = *(const f32x4*)sp, b = *(const f32x4*)(sp + 4), c = *(const f32x4*)(sp + 8), d = *(const f32x4*)(sp + 12);
;               const f32x4 q = (a + b) + (c + d); rsL[t] = rsqrtf(((q[0] + q[1]) + (q[2] + q[3])) * (1.0f / 1024.0f) + EPS); }
	s_add_u32 s10, s84, 0x80
	ds_read_b128 v[68:71], v224
	ds_read_b128 v[84:87], v224 offset:1024
	ds_read_b128 v[88:91], v224 offset:2048
	ds_read_b128 v[92:95], v224 offset:3072
	s_addc_u32 s11, s85, 0
	s_mov_b32 m0, s88
	s_nop 0
	global_load_lds_dwordx4 v217, s[10:11]
	s_mov_b32 m0, s89
	s_nop 0
	global_load_lds_dwordx4 v219, s[10:11]
	s_mov_b32 m0, s95
	s_nop 0
	global_load_lds_dwordx4 v216, s[16:17]
	s_mov_b32 m0, s37
	s_nop 0
	global_load_lds_dwordx4 v218, s[16:17]
	s_add_u32 s10, s14, 0x40080
	s_addc_u32 s11, s15, 0
	s_mov_b32 m0, s56
	s_nop 0
	global_load_lds_dwordx4 v216, s[10:11]
	s_mov_b32 m0, s57
	s_nop 0
	global_load_lds_dwordx4 v218, s[10:11]
	s_waitcnt vmcnt(8)
	s_waitcnt lgkmcnt(0)
	s_barrier
	s_setprio 1
	s_waitcnt lgkmcnt(3)
	v_mfma_f32_16x16x32_bf16 v[72:75], v[68:71], v[132:135], v[72:75]
	s_waitcnt lgkmcnt(1)
	v_mfma_f32_16x16x32_bf16 v[56:59], v[88:91], v[132:135], v[56:59]
	v_mfma_f32_16x16x32_bf16 v[96:99], v[68:71], v[152:155], v[96:99]
	v_mfma_f32_16x16x32_bf16 v[72:75], v[84:87], v[140:143], v[72:75]
	s_waitcnt lgkmcnt(0)
	v_mfma_f32_16x16x32_bf16 v[56:59], v[92:95], v[140:143], v[56:59]
	v_mfma_f32_16x16x32_bf16 v[140:143], v[84:87], v[156:159], v[96:99]
	v_mfma_f32_16x16x32_bf16 v[96:99], v[68:71], v[166:169], v[100:103]
	v_mfma_f32_16x16x32_bf16 v[132:135], v[84:87], v[178:181], v[96:99]
	v_mfma_f32_16x16x32_bf16 v[96:99], v[68:71], v[182:185], v[128:131]
	v_mfma_f32_16x16x32_bf16 v[128:131], v[84:87], v[186:189], v[96:99]
	v_mfma_f32_16x16x32_bf16 v[96:99], v[68:71], v[190:193], v[116:119]
	v_mfma_f32_16x16x32_bf16 v[116:119], v[84:87], v[194:197], v[96:99]
	v_mfma_f32_16x16x32_bf16 v[96:99], v[68:71], v[198:201], v[108:111]
	v_mfma_f32_16x16x32_bf16 v[44:47], v[88:91], v[152:155], v[44:47]
	v_mfma_f32_16x16x32_bf16 v[36:39], v[88:91], v[166:169], v[36:39]
	v_mfma_f32_16x16x32_bf16 v[32:35], v[88:91], v[182:185], v[32:35]
	v_mfma_f32_16x16x32_bf16 v[20:23], v[88:91], v[190:193], v[20:23]
	v_mfma_f32_16x16x32_bf16 v[108:111], v[84:87], v[202:205], v[96:99]
	v_mfma_f32_16x16x32_bf16 v[12:15], v[88:91], v[198:201], v[12:15]
	v_mfma_f32_16x16x32_bf16 v[96:99], v[68:71], v[226:229], v[104:107]
	v_mfma_f32_16x16x32_bf16 v[8:11], v[88:91], v[226:229], v[8:11]
	v_mfma_f32_16x16x32_bf16 v[60:63], v[68:71], v[234:237], v[60:63]
	v_mfma_f32_16x16x32_bf16 v[0:3], v[88:91], v[234:237], v[0:3]
	v_mfma_f32_16x16x32_bf16 v[44:47], v[92:95], v[156:159], v[44:47]
	v_mfma_f32_16x16x32_bf16 v[36:39], v[92:95], v[178:181], v[36:39]
	v_mfma_f32_16x16x32_bf16 v[32:35], v[92:95], v[186:189], v[32:35]
	v_mfma_f32_16x16x32_bf16 v[20:23], v[92:95], v[194:197], v[20:23]
	v_mfma_f32_16x16x32_bf16 v[12:15], v[92:95], v[202:205], v[12:15]
	v_mfma_f32_16x16x32_bf16 v[104:107], v[84:87], v[230:233], v[96:99]
	v_mfma_f32_16x16x32_bf16 v[8:11], v[92:95], v[230:233], v[8:11]
	v_mfma_f32_16x16x32_bf16 v[60:63], v[84:87], v[238:241], v[60:63]
	v_mfma_f32_16x16x32_bf16 v[0:3], v[92:95], v[238:241], v[0:3]
	s_setprio 0
	s_barrier
	s_add_i32 s69, s69, 2
	s_add_u32 vcc_hi, vcc_hi, 0x100
	s_addc_u32 s68, s68, 0
	s_cmp_gt_u32 s69, 13
	s_mov_b64 s[10:11], s[12:13]
	s_cbranch_scc0 .LBB0_1027
	s_and_b64 vcc, exec, s[90:91]
	s_cbranch_vccz .LBB0_1030
	v_lshlrev_b32_e32 v68, 4, v215
	v_add3_u32 v68, v214, s59, v68
	s_ashr_i32 s97, s96, 31
	s_lshl_b64 s[12:13], s[96:97], 14
	v_ashrrev_i32_e32 v69, 31, v68
	s_add_u32 s12, s18, s12
	s_addc_u32 s13, s19, s13
	v_lshlrev_b64 v[70:71], 6, v[68:69]
	v_lshl_add_u64 v[70:71], s[12:13], 0, v[70:71]
	global_load_dwordx4 v[86:89], v[70:71], off
	global_load_dwordx4 v[90:93], v[70:71], off offset:16
	global_load_dwordx4 v[94:97], v[70:71], off offset:32
	global_load_dwordx4 v[98:101], v[70:71], off offset:48
	s_barrier

;     __device__ __forceinline__ void operator()(f32x4 (&acc)[2][2][4][2], const Unit& u, int wr, int wc, int fr, int fq) const {
;     ...
;         { const int t = (wc * 4 + fq) * 16 + fr;
;           if (wr == 0) { const float* sp = ssq + ((size_t)u.pm * 256 + t) * 16; const f32x4 a = *(const f32x4*)sp, b = *(const f32x4*)(sp + 4), c = *(const f32x4*)(sp + 8), d = *(const f32x4*)(sp + 12);
;               const f32x4 q = (a + b) + (c + d); rsL[t] = rsqrtf(((q[0] + q[1]) + (q[2] + q[3])) * (1.0f / 1024.0f) + EPS); }
.LBB0_1034:
	s_and_b64 vcc, exec, s[12:13]
	s_cbranch_vccz .LBB0_1036
	s_ashr_i32 s97, s96, 31
	s_lshl_b64 s[12:13], s[96:97], 14
	v_ashrrev_i32_e32 v69, 31, v68
	s_add_u32 s12, s18, s12
	s_addc_u32 s13, s19, s13
	v_lshlrev_b64 v[70:71], 6, v[68:69]
	v_lshl_add_u64 v[70:71], s[12:13], 0, v[70:71]
	v_lshl_add_u32 v68, v68, 2, 0
	v_add_u32_e32 v68, 0x22040, v68
	s_waitcnt vmcnt(2)
	v_pk_add_f32 v[70:71], v[88:89], v[92:93]
	v_pk_add_f32 v[86:87], v[86:87], v[90:91]
	s_waitcnt vmcnt(0)
	v_pk_add_f32 v[88:89], v[96:97], v[100:101]
	v_pk_add_f32 v[90:91], v[94:95], v[98:99]
	v_pk_add_f32 v[70:71], v[70:71], v[88:89]
	v_pk_add_f32 v[86:87], v[86:87], v[90:91]
	s_nop 0
	v_pk_mov_b32 v[88:89], v[86:87], v[70:71] op_sel:[1,0]
	v_mov_b32_e32 v87, v71
	v_pk_add_f32 v[70:71], v[88:89], v[86:87]
	s_nop 0
	v_add_f32_e32 v69, v70, v71
	v_fmamk_f32 v69, v69, 0x3a800000, v208
	v_mul_f32_e32 v70, 0x4b800000, v69
	v_cmp_gt_f32_e32 vcc, s44, v69
	s_nop 1
	v_cndmask_b32_e32 v69, v69, v70, vcc
	v_rsq_f32_e32 v69, v69
	s_nop 0
	v_mul_f32_e32 v70, 0x45800000, v69
	v_cndmask_b32_e32 v69, v69, v70, vcc
	ds_write_b32 v68, v69
